# attention: selection mask by bfe+bfi, lazy softmax reference (skip O rescale when alpha==1), prompt units request K/V two tiles ahead; plus P10 hand loop
# speedup vs baseline: 1.0058x; 1.0030x over previous
; __device__ __forceinline__ void attn_unit(const Frame& F, int l, int samp, int b, int c, int g) {
;     ...
;     f32x16 o[4];
; #pragma unroll
;     for (int d = 0; d < 4; ++d)
; #pragma unroll
;         for (int i = 0; i < 16; ++i) o[d][i] = 0.f;
;     float mrun = -INFINITY, lsum = 0.f;
;     const float* CKf = A.in[I_CK] + ((size_t)(l * DB + b) * PAST) * 256 + g * 128; const float* CVf = A.in[I_CV] + ((size_t)(l * DB + b) * PAST) * 256 + g * 128;
;     u32x4 kr[4], vr[4]; u64 mwn = 0ull, mwc;
;     const int vp = tid & 31, vch = tid >> 5;
;     ...
;     ATT_LOAD(0);
;     ATT_WRITE(0, 0); mwc = mwn;
;     __syncthreads();
;     for (int t = 0; t < ntiles; ++t) {
.LBB0_1543:
	s_add_i32 s0, s33, 1
	s_and_b32 s22, s0, 0x3ffffff
	s_and_b64 s[0:1], s[16:17], exec
	s_movk_i32 s0, 0x110
	v_lshlrev_b32_e32 v20, 4, v20
	v_mul_lo_u32 v206, v10, s0
	v_and_b32_e32 v207, 0xf0, v20
	v_add3_u32 v20, 0, v206, v207
	v_mul_lo_u32 v208, v12, s0
	s_movk_i32 s0, 0x440
	ds_write_b128 v20, v[0:3]
	v_add3_u32 v0, 0, v208, v207
	v_lshlrev_b32_e32 v209, 2, v9
	v_mul_lo_u32 v210, v23, s0
	ds_write_b128 v0, v[4:7]
	v_lshlrev_b32_e32 v0, 16, v28
	s_mov_b32 s1, 0xffff
	v_add3_u32 v1, 0, v210, v209
	v_lshrrev_b32_e32 v2, 16, v26
	v_and_or_b32 v0, v26, s1, v0
	v_and_or_b32 v2, v28, s79, v2
	v_add_u32_e32 v1, 0x8800, v1
	ds_write2_b32 v1, v0, v2 offset1:34
	v_lshlrev_b32_e32 v0, 16, v27
	v_lshrrev_b32_e32 v2, 16, v24
	v_and_or_b32 v0, v24, s1, v0
	v_and_or_b32 v2, v27, s79, v2
	ds_write2_b32 v1, v0, v2 offset0:68 offset1:102
	v_lshlrev_b32_e32 v0, 16, v25
	v_lshrrev_b32_e32 v2, 16, v13
	v_and_or_b32 v0, v13, s1, v0
	v_and_or_b32 v2, v25, s79, v2
	s_cselect_b32 s22, 33, s22
	ds_write2_b32 v1, v0, v2 offset0:136 offset1:170
	v_lshlrev_b32_e32 v0, 16, v17
	v_lshrrev_b32_e32 v2, 16, v11
	v_and_or_b32 v0, v11, s1, v0
	v_and_or_b32 v2, v17, s79, v2
	s_cmp_lg_u32 s22, 0
	v_lshlrev_b32_e32 v179, 2, v22
	ds_write2_b32 v1, v0, v2 offset0:204 offset1:238
	s_waitcnt lgkmcnt(0)
	s_barrier
	s_cbranch_scc0 .LBB0_1568
	s_mov_b64 s[0:1], 0x49bd0008
	v_mul_u32_u24_e32 v0, 0x110, v21
	v_lshlrev_b32_e32 v1, 4, v22
	v_lshl_add_u64 v[188:189], v[18:19], 0, s[0:1]
	s_add_u32 s0, s36, s18
	v_lshl_add_u64 v[182:183], s[20:21], 0, v[200:201]
	v_add3_u32 v211, 0, v0, v1
	v_mul_u32_u24_e32 v0, 0x88, v21
	v_lshlrev_b32_e32 v200, 10, v9
	s_addc_u32 s1, 0, s19
	v_add3_u32 v212, 0, v8, v0
	v_lshl_add_u64 v[0:1], s[0:1], 0, v[200:201]
	v_lshl_add_u64 v[0:1], v[14:15], 1, v[0:1]
	v_mov_b32_e32 v17, v201
	v_lshl_add_u64 v[190:191], s[70:71], 1, v[0:1]
	v_mov_b32_e32 v0, 0x4000
	v_mov_b32_e32 v213, 0
	v_lshl_add_u64 v[184:185], s[4:5], 0, v[16:17]
	v_lshl_add_u64 v[186:187], v[14:15], 2, s[6:7]
	v_lshlrev_b32_e32 v178, 2, v22
	v_add_u32_e32 v192, 64, v12
	v_add_u32_e32 v194, 64, v10
	v_lshl_or_b32 v200, v9, 9, v0
	s_mov_b32 s6, 0
	v_mov_b32_e32 v216, 0xff800000
	s_waitcnt vmcnt(0)
	v_mov_b64_e32 v[196:197], v[180:181]
	v_mov_b32_e32 v0, 0
	v_mov_b32_e32 v1, v213
	v_mov_b32_e32 v2, v213
	v_mov_b32_e32 v3, v213
	v_mov_b32_e32 v4, v213
	v_mov_b32_e32 v5, v213
	v_mov_b32_e32 v6, v213
	v_mov_b32_e32 v7, v213
	v_mov_b32_e32 v8, v213
	v_mov_b32_e32 v9, v213
	v_mov_b32_e32 v10, v213
	v_mov_b32_e32 v11, v213
	v_mov_b32_e32 v12, v213
	v_mov_b32_e32 v13, v213
	v_mov_b32_e32 v14, v213
	v_mov_b32_e32 v15, v213
	v_mov_b32_e32 v16, 0
	v_mov_b32_e32 v17, v213
	v_mov_b32_e32 v18, v213
	v_mov_b32_e32 v19, v213
	v_mov_b32_e32 v20, v213
	v_mov_b32_e32 v21, v213
	v_mov_b32_e32 v22, v213
	v_mov_b32_e32 v23, v213
	v_mov_b32_e32 v24, v213
	v_mov_b32_e32 v25, v213
	v_mov_b32_e32 v26, v213
	v_mov_b32_e32 v27, v213
	v_mov_b32_e32 v28, v213
	v_mov_b32_e32 v29, v213
	v_mov_b32_e32 v30, v213
	v_mov_b32_e32 v31, v213
	v_mov_b32_e32 v32, 0
	v_mov_b32_e32 v33, v213
	v_mov_b32_e32 v34, v213
	v_mov_b32_e32 v35, v213
	v_mov_b32_e32 v36, v213
	v_mov_b32_e32 v37, v213
	v_mov_b32_e32 v38, v213
	v_mov_b32_e32 v39, v213
	v_mov_b32_e32 v40, v213
	v_mov_b32_e32 v41, v213
	v_mov_b32_e32 v42, v213
	v_mov_b32_e32 v43, v213
	v_mov_b32_e32 v44, v213
	v_mov_b32_e32 v45, v213
	v_mov_b32_e32 v46, v213
	v_mov_b32_e32 v47, v213
	v_mov_b32_e32 v48, 0
	v_mov_b32_e32 v49, v213
	v_mov_b32_e32 v50, v213
	v_mov_b32_e32 v51, v213
	v_mov_b32_e32 v52, v213
	v_mov_b32_e32 v53, v213
	v_mov_b32_e32 v54, v213
	v_mov_b32_e32 v55, v213
	v_mov_b32_e32 v56, v213
	v_mov_b32_e32 v57, v213
	v_mov_b32_e32 v58, v213
	v_mov_b32_e32 v59, v213
	v_mov_b32_e32 v60, v213
	v_mov_b32_e32 v61, v213
	v_mov_b32_e32 v62, v213
	v_mov_b32_e32 v63, v213
	s_cmp_eq_u64 s[16:17], 0
	s_cbranch_scc1 .Lad_pre

.LBB0_1551:
	s_and_b32 s4, s6, 1
	s_mul_i32 s5, s4, 0x4400
	v_add_u32_e32 v193, s5, v211
	ds_read_b128 v[64:67], v193 offset:224
	ds_read_b128 v[68:71], v193 offset:192
	ds_read_b128 v[72:75], v193 offset:160
	ds_read_b128 v[76:79], v193 offset:128
	ds_read_b128 v[160:163], v193 offset:96
	ds_read_b128 v[164:167], v193 offset:64
	ds_read_b128 v[80:83], v193
	ds_read_b128 v[168:171], v193 offset:32
	v_lshrrev_b64 v[196:197], v178, v[196:197]
	s_waitcnt lgkmcnt(0)
	s_nop 0
	v_mfma_f32_32x32x16_bf16 v[80:95], v[80:83], v[120:123], 0
	v_mfma_f32_32x32x16_bf16 v[80:95], v[168:171], v[96:99], v[80:95]
	v_mfma_f32_32x32x16_bf16 v[80:95], v[164:167], v[100:103], v[80:95]
	v_mfma_f32_32x32x16_bf16 v[80:95], v[160:163], v[104:107], v[80:95]
	v_mfma_f32_32x32x16_bf16 v[80:95], v[76:79], v[108:111], v[80:95]
	v_mfma_f32_32x32x16_bf16 v[80:95], v[72:75], v[112:115], v[80:95]
	v_mfma_f32_32x32x16_bf16 v[80:95], v[68:71], v[116:119], v[80:95]
	v_mfma_f32_32x32x16_bf16 v[80:95], v[64:67], v[124:127], v[80:95]
	ds_read_b128 v[160:163], v193 offset:8928
	ds_read_b128 v[164:167], v193 offset:8896
	ds_read_b128 v[168:171], v193 offset:8864
	ds_read_b128 v[172:175], v193 offset:8832
	ds_read_b128 v[202:205], v193 offset:8800
	ds_read_b128 v[218:221], v193 offset:8768
	ds_read_b128 v[64:67], v193 offset:8704
	ds_read_b128 v[224:227], v193 offset:8736
	s_waitcnt lgkmcnt(0)
	s_nop 0
	v_mfma_f32_32x32x16_bf16 v[64:79], v[64:67], v[120:123], 0
	v_mfma_f32_32x32x16_bf16 v[64:79], v[224:227], v[96:99], v[64:79]
	v_mfma_f32_32x32x16_bf16 v[64:79], v[218:221], v[100:103], v[64:79]
	v_mfma_f32_32x32x16_bf16 v[64:79], v[202:205], v[104:107], v[64:79]
	v_bfe_i32 v230, v196, 0, 1
	v_bfe_i32 v202, v196, 1, 1
	v_bfi_b32 v80, v230, v80, v241
	v_bfi_b32 v202, v202, v81, v241
	v_bfe_i32 v203, v196, 2, 1
	v_bfe_i32 v204, v196, 3, 1
	v_bfi_b32 v203, v203, v82, v241
	v_bfi_b32 v204, v204, v83, v241
	v_mfma_f32_32x32x16_bf16 v[64:79], v[172:175], v[108:111], v[64:79]
	v_bfe_i32 v205, v196, 8, 1
	v_bfe_i32 v217, v196, 9, 1
	v_bfi_b32 v205, v205, v84, v241
	v_bfi_b32 v217, v217, v85, v241
	v_bfe_i32 v218, v196, 10, 1
	v_bfe_i32 v219, v196, 11, 1
	v_bfi_b32 v218, v218, v86, v241
	v_bfi_b32 v219, v219, v87, v241
	v_mfma_f32_32x32x16_bf16 v[64:79], v[168:171], v[112:115], v[64:79]
	v_bfe_i32 v220, v196, 16, 1
	v_bfe_i32 v221, v196, 17, 1
	v_bfi_b32 v220, v220, v88, v241
	v_bfi_b32 v221, v221, v89, v241
	v_bfe_i32 v224, v196, 18, 1
	v_bfe_i32 v225, v196, 19, 1
	v_bfi_b32 v224, v224, v90, v241
	v_bfi_b32 v225, v225, v91, v241
	v_mfma_f32_32x32x16_bf16 v[64:79], v[164:167], v[116:119], v[64:79]
	v_bfe_i32 v226, v196, 24, 1
	v_bfe_i32 v227, v196, 25, 1
	v_bfi_b32 v226, v226, v92, v241
	v_bfi_b32 v227, v227, v93, v241
	v_bfe_i32 v228, v196, 26, 1
	v_bfe_i32 v229, v196, 27, 1
	v_bfi_b32 v228, v228, v94, v241
	v_bfi_b32 v229, v229, v95, v241
	v_mfma_f32_32x32x16_bf16 v[64:79], v[160:163], v[124:127], v[64:79]
	v_max3_f32 v81, v80, s80, v202
	v_max3_f32 v81, v81, v203, v204
	v_max3_f32 v81, v81, v205, v217
	v_max3_f32 v81, v81, v218, v219
	v_max3_f32 v81, v81, v220, v221
	v_max3_f32 v81, v81, v224, v225
	v_max3_f32 v81, v81, v226, v227
	v_max3_f32 v81, v81, v228, v229
	v_add_u32_e32 v160, s5, v212
	v_add_u32_e32 v215, 0x8800, v160
	v_add_u32_e32 v214, 0x9800, v160
	v_add_u32_e32 v195, 0xa800, v160
	v_add_u32_e32 v193, 0xb800, v160
	ds_read2_b64 v[172:175], v215 offset1:2
	ds_read2_b64 v[168:171], v214 offset0:32 offset1:34
	ds_read2_b64 v[164:167], v195 offset0:64 offset1:66
	ds_read2_b64 v[160:163], v193 offset0:96 offset1:98
	v_bfe_i32 v83, v197, 0, 1
	v_bfe_i32 v84, v197, 1, 1
	v_bfi_b32 v64, v83, v64, v241
	v_bfi_b32 v65, v84, v65, v241
	v_max3_f32 v81, v81, v64, v65
	v_bfe_i32 v83, v197, 2, 1
	v_bfe_i32 v84, v197, 3, 1
	v_bfi_b32 v66, v83, v66, v241
	v_bfi_b32 v67, v84, v67, v241
	v_max3_f32 v81, v81, v66, v67
	v_bfe_i32 v83, v197, 8, 1
	v_bfe_i32 v84, v197, 9, 1
	v_bfi_b32 v68, v83, v68, v241
	v_bfi_b32 v69, v84, v69, v241
	v_max3_f32 v81, v81, v68, v69
	v_bfe_i32 v83, v197, 10, 1
	v_bfe_i32 v84, v197, 11, 1
	v_bfi_b32 v70, v83, v70, v241
	v_bfi_b32 v71, v84, v71, v241
	v_max3_f32 v81, v81, v70, v71
	v_bfe_i32 v83, v197, 16, 1
	v_bfe_i32 v84, v197, 17, 1
	v_bfi_b32 v72, v83, v72, v241
	v_bfi_b32 v73, v84, v73, v241
	v_max3_f32 v81, v81, v72, v73
	v_bfe_i32 v83, v197, 18, 1
	v_bfe_i32 v84, v197, 19, 1
	v_bfi_b32 v74, v83, v74, v241
	v_bfi_b32 v75, v84, v75, v241
	v_max3_f32 v81, v81, v74, v75
	v_bfe_i32 v83, v197, 24, 1
	v_bfe_i32 v84, v197, 25, 1
	v_bfi_b32 v76, v83, v76, v241
	v_bfi_b32 v77, v84, v77, v241
	v_max3_f32 v81, v81, v76, v77
	v_bfe_i32 v83, v197, 26, 1
	v_bfe_i32 v84, v197, 27, 1
	v_bfi_b32 v78, v83, v78, v241
	v_bfi_b32 v79, v84, v79, v241
	v_max3_f32 v81, v81, v78, v79
	v_mbcnt_lo_u32_b32 v82, -1, 0
	v_mbcnt_hi_u32_b32 v82, -1, v82
	s_nop 0
	v_lshlrev_b32_e32 v82, 2, v82
	v_xor_b32_e32 v82, 0x80, v82
	ds_bpermute_b32 v82, v82, v81
	s_waitcnt lgkmcnt(0)
	v_max3_f32 v81, v216, v81, v82
	v_add_f32_e32 v82, 0x41000000, v216
	v_cmp_gt_f32_e32 vcc, v81, v82
	s_nop 1
	s_cbranch_vccnz .Latt_newref
	v_mov_b32_e32 v81, v216
.Latt_newref:
	v_cmp_neq_f32_e32 vcc, s80, v81
	s_nop 1
	v_cndmask_b32_e32 v230, 0, v81, vcc
	v_sub_f32_e32 v80, v80, v230
	v_exp_f32_e32 v82, v80
	v_sub_f32_e32 v80, v202, v230
	v_exp_f32_e32 v83, v80
	v_sub_f32_e32 v80, v203, v230
	v_exp_f32_e32 v84, v80
	v_sub_f32_e32 v80, v204, v230
	v_exp_f32_e32 v85, v80
	v_sub_f32_e32 v80, v205, v230
	v_sub_f32_e32 v64, v64, v230
	v_sub_f32_e32 v231, v216, v230
	v_exp_f32_e32 v86, v80
	v_sub_f32_e32 v80, v217, v230
	v_exp_f32_e32 v216, v64
	v_sub_f32_e32 v64, v65, v230
	v_exp_f32_e32 v87, v80
	v_sub_f32_e32 v80, v218, v230
	v_exp_f32_e32 v217, v64
	v_sub_f32_e32 v64, v66, v230
	v_exp_f32_e32 v88, v80
	v_sub_f32_e32 v80, v219, v230
	v_exp_f32_e32 v218, v64
	v_sub_f32_e32 v64, v67, v230
	v_exp_f32_e32 v89, v80
	v_sub_f32_e32 v80, v220, v230
	v_exp_f32_e32 v219, v64
	v_sub_f32_e32 v64, v68, v230
	v_exp_f32_e32 v90, v80
	v_sub_f32_e32 v80, v221, v230
	v_exp_f32_e32 v220, v64
	v_sub_f32_e32 v64, v69, v230
	v_exp_f32_e32 v91, v80
	v_sub_f32_e32 v80, v224, v230
	v_exp_f32_e32 v221, v64
	v_sub_f32_e32 v64, v70, v230
	v_exp_f32_e32 v92, v80
	v_sub_f32_e32 v80, v225, v230
	v_exp_f32_e32 v242, v64
	v_sub_f32_e32 v64, v71, v230
	v_exp_f32_e32 v93, v80
	v_sub_f32_e32 v80, v226, v230
	v_exp_f32_e32 v243, v64
	v_sub_f32_e32 v64, v72, v230
	v_exp_f32_e32 v94, v80
	v_sub_f32_e32 v80, v227, v230
	v_exp_f32_e32 v244, v64
	v_sub_f32_e32 v64, v73, v230
	v_exp_f32_e32 v95, v80
	v_sub_f32_e32 v80, v228, v230
	v_exp_f32_e32 v245, v64
	v_sub_f32_e32 v64, v74, v230
	v_exp_f32_e32 v196, v80
	v_sub_f32_e32 v80, v229, v230
	v_exp_f32_e32 v246, v64
	v_sub_f32_e32 v64, v75, v230
	v_exp_f32_e32 v197, v80
	v_exp_f32_e32 v247, v64
	v_sub_f32_e32 v64, v76, v230
	v_exp_f32_e32 v80, v231
	v_exp_f32_e32 v248, v64
	v_sub_f32_e32 v64, v77, v230
	v_exp_f32_e32 v249, v64
	v_sub_f32_e32 v64, v78, v230
	v_exp_f32_e32 v250, v64
	v_sub_f32_e32 v64, v79, v230
	v_exp_f32_e32 v251, v64
	v_cvt_pk_bf16_f32 v64, v82, v83
	v_cvt_pk_bf16_f32 v65, v84, v85
	v_cvt_pk_bf16_f32 v66, v86, v87
	v_cvt_pk_bf16_f32 v67, v88, v89
	v_cmp_neq_f32_e32 vcc, 1.0, v80
	s_nop 1
	s_cbranch_vccz .Latt_norescale
	v_pk_mul_f32 v[14:15], v[14:15], v[80:81] op_sel_hi:[1,0]
	v_pk_mul_f32 v[12:13], v[12:13], v[80:81] op_sel_hi:[1,0]
	v_pk_mul_f32 v[10:11], v[10:11], v[80:81] op_sel_hi:[1,0]
	v_pk_mul_f32 v[8:9], v[8:9], v[80:81] op_sel_hi:[1,0]
	v_pk_mul_f32 v[6:7], v[6:7], v[80:81] op_sel_hi:[1,0]
	v_pk_mul_f32 v[4:5], v[4:5], v[80:81] op_sel_hi:[1,0]
	v_pk_mul_f32 v[2:3], v[2:3], v[80:81] op_sel_hi:[1,0]
	v_pk_mul_f32 v[0:1], v[0:1], v[80:81] op_sel_hi:[1,0]
	v_pk_mul_f32 v[30:31], v[30:31], v[80:81] op_sel_hi:[1,0]
	v_pk_mul_f32 v[28:29], v[28:29], v[80:81] op_sel_hi:[1,0]
	v_pk_mul_f32 v[26:27], v[26:27], v[80:81] op_sel_hi:[1,0]
	v_pk_mul_f32 v[24:25], v[24:25], v[80:81] op_sel_hi:[1,0]
	v_pk_mul_f32 v[22:23], v[22:23], v[80:81] op_sel_hi:[1,0]
	v_pk_mul_f32 v[20:21], v[20:21], v[80:81] op_sel_hi:[1,0]
	v_pk_mul_f32 v[18:19], v[18:19], v[80:81] op_sel_hi:[1,0]
	v_pk_mul_f32 v[16:17], v[16:17], v[80:81] op_sel_hi:[1,0]
	v_pk_mul_f32 v[46:47], v[46:47], v[80:81] op_sel_hi:[1,0]
	v_pk_mul_f32 v[44:45], v[44:45], v[80:81] op_sel_hi:[1,0]
	v_pk_mul_f32 v[42:43], v[42:43], v[80:81] op_sel_hi:[1,0]
	v_pk_mul_f32 v[40:41], v[40:41], v[80:81] op_sel_hi:[1,0]
	v_pk_mul_f32 v[38:39], v[38:39], v[80:81] op_sel_hi:[1,0]
	v_pk_mul_f32 v[36:37], v[36:37], v[80:81] op_sel_hi:[1,0]
	v_pk_mul_f32 v[34:35], v[34:35], v[80:81] op_sel_hi:[1,0]
	v_pk_mul_f32 v[32:33], v[32:33], v[80:81] op_sel_hi:[1,0]
	v_pk_mul_f32 v[62:63], v[62:63], v[80:81] op_sel_hi:[1,0]
	v_pk_mul_f32 v[60:61], v[60:61], v[80:81] op_sel_hi:[1,0]
	v_pk_mul_f32 v[58:59], v[58:59], v[80:81] op_sel_hi:[1,0]
	v_pk_mul_f32 v[56:57], v[56:57], v[80:81] op_sel_hi:[1,0]
	v_pk_mul_f32 v[54:55], v[54:55], v[80:81] op_sel_hi:[1,0]
	v_pk_mul_f32 v[52:53], v[52:53], v[80:81] op_sel_hi:[1,0]
	v_pk_mul_f32 v[50:51], v[50:51], v[80:81] op_sel_hi:[1,0]
	v_pk_mul_f32 v[48:49], v[48:49], v[80:81] op_sel_hi:[1,0]
; __device__ __forceinline__ void attn_unit(const Frame& F, int l, int samp, int b, int c, int g) {
;     ...
;     ATT_LOAD(0);
;     ATT_WRITE(0, 0); mwc = mwn;
;     __syncthreads();
;     for (int t = 0; t < ntiles; ++t) {
;         const int buf = t & 1;
;         if (t + 1 < ntiles) ATT_LOAD(t + 1);
;         ATT_COMPUTE(buf, mwc);
;         if (t + 1 < ntiles) ATT_WRITE(buf ^ 1, t + 1);
.Latt_norescale:
	ds_read2_b64 v[68:71], v215 offset0:4 offset1:6
	ds_read2_b64 v[72:75], v214 offset0:36 offset1:38
	ds_read2_b64 v[76:79], v195 offset0:68 offset1:70
	ds_read2_b64 v[202:205], v193 offset0:100 offset1:102
	s_andn2_b64 vcc, exec, s[0:1]
	v_mfma_f32_32x32x16_bf16 v[48:63], v[172:175], v[64:67], v[48:63]
	v_mfma_f32_32x32x16_bf16 v[32:47], v[168:171], v[64:67], v[32:47]
	v_mfma_f32_32x32x16_bf16 v[16:31], v[164:167], v[64:67], v[16:31]
	v_mfma_f32_32x32x16_bf16 v[0:15], v[160:163], v[64:67], v[0:15]
	v_cvt_pk_bf16_f32 v64, v90, v91
	v_cvt_pk_bf16_f32 v65, v92, v93
	v_cvt_pk_bf16_f32 v66, v94, v95
	v_cvt_pk_bf16_f32 v67, v196, v197
	ds_read2_b64 v[160:163], v215 offset0:8 offset1:10
	ds_read2_b64 v[164:167], v214 offset0:40 offset1:42
	ds_read2_b64 v[168:171], v195 offset0:72 offset1:74
	ds_read2_b64 v[172:175], v193 offset0:104 offset1:106
	s_waitcnt lgkmcnt(4)
	s_nop 0
	v_mfma_f32_32x32x16_bf16 v[48:63], v[68:71], v[64:67], v[48:63]
	v_mfma_f32_32x32x16_bf16 v[32:47], v[72:75], v[64:67], v[32:47]
	v_mfma_f32_32x32x16_bf16 v[16:31], v[76:79], v[64:67], v[16:31]
	v_mfma_f32_32x32x16_bf16 v[0:15], v[202:205], v[64:67], v[0:15]
	v_cvt_pk_bf16_f32 v64, v216, v217
	v_cvt_pk_bf16_f32 v65, v218, v219
	v_cvt_pk_bf16_f32 v66, v220, v221
	v_cvt_pk_bf16_f32 v67, v242, v243
	ds_read2_b64 v[68:71], v215 offset0:12 offset1:14
	ds_read2_b64 v[72:75], v214 offset0:44 offset1:46
	ds_read2_b64 v[76:79], v195 offset0:76 offset1:78
	ds_read2_b64 v[202:205], v193 offset0:108 offset1:110
	s_waitcnt lgkmcnt(4)
	s_waitcnt lgkmcnt(0)
	v_mfma_f32_32x32x16_bf16 v[48:63], v[160:163], v[64:67], v[48:63]
	v_mfma_f32_32x32x16_bf16 v[32:47], v[164:167], v[64:67], v[32:47]
	v_mfma_f32_32x32x16_bf16 v[16:31], v[168:171], v[64:67], v[16:31]
	v_mfma_f32_32x32x16_bf16 v[0:15], v[172:175], v[64:67], v[0:15]
	v_cvt_pk_bf16_f32 v64, v244, v245
	v_cvt_pk_bf16_f32 v65, v246, v247
	v_cvt_pk_bf16_f32 v66, v248, v249
	v_cvt_pk_bf16_f32 v67, v250, v251
	s_nop 1
	v_mfma_f32_32x32x16_bf16 v[48:63], v[68:71], v[64:67], v[48:63]
	v_mfma_f32_32x32x16_bf16 v[32:47], v[72:75], v[64:67], v[32:47]
	v_mfma_f32_32x32x16_bf16 v[16:31], v[76:79], v[64:67], v[16:31]
	v_mfma_f32_32x32x16_bf16 v[0:15], v[202:205], v[64:67], v[0:15]
	s_cbranch_vccnz .LBB0_1555
	s_cmp_lt_u32 s6, 31
	s_cselect_b64 s[0:1], -1, 0
	s_and_b64 s[0:1], s[16:17], s[0:1]
	s_waitcnt vmcnt(4)
	v_mov_b64_e32 v[68:69], v[144:145]
	s_waitcnt vmcnt(3)
	v_mov_b64_e32 v[76:77], v[148:149]
	s_waitcnt vmcnt(1)
	v_mov_b64_e32 v[64:65], v[156:157]
	v_mov_b64_e32 v[72:73], v[152:153]
	s_andn2_b64 vcc, exec, s[0:1]
	v_mov_b64_e32 v[70:71], v[146:147]
	v_mov_b64_e32 v[78:79], v[150:151]
	v_mov_b64_e32 v[66:67], v[158:159]
	v_mov_b64_e32 v[74:75], v[154:155]
	s_cbranch_vccnz .LBB0_1554
	v_cvt_pk_bf16_f32 v68, v144, v145
	v_cvt_pk_bf16_f32 v69, v146, v147
	v_cvt_pk_bf16_f32 v70, v148, v149
	v_cvt_pk_bf16_f32 v71, v150, v151
	v_cvt_pk_bf16_f32 v76, v132, v133
	v_cvt_pk_bf16_f32 v77, v134, v135
	v_cvt_pk_bf16_f32 v78, v128, v129
	v_cvt_pk_bf16_f32 v79, v130, v131
	v_cvt_pk_bf16_f32 v64, v156, v157
	v_cvt_pk_bf16_f32 v65, v158, v159
	v_cvt_pk_bf16_f32 v66, v152, v153
	v_cvt_pk_bf16_f32 v67, v154, v155
	v_cvt_pk_bf16_f32 v72, v140, v141
	v_cvt_pk_bf16_f32 v73, v142, v143
	v_cvt_pk_bf16_f32 v74, v136, v137
	v_cvt_pk_bf16_f32 v75, v138, v139

; __device__ __forceinline__ void attn_unit(const Frame& F, int l, int samp, int b, int c, int g) {
;     ...
;     for (int t = 0; t < ntiles; ++t) {
;         const int buf = t & 1;
;         if (t + 1 < ntiles) ATT_LOAD(t + 1);
.Lad_pre:
	s_cmp_lt_u32 s22, 2
	s_cbranch_scc1 .Lad_1545
	v_ashrrev_i32_e32 v195, 31, v194
	v_ashrrev_i32_e32 v193, 31, v192
	v_lshlrev_b64 v[64:65], 9, v[194:195]
	v_lshl_add_u64 v[66:67], v[182:183], 0, v[64:65]
	v_lshlrev_b64 v[64:65], 9, v[192:193]
	v_lshl_add_u64 v[70:71], s[12:13], 0, v[190:191]
	s_mov_b64 s[4:5], 0x8200
	v_lshl_add_u64 v[68:69], v[182:183], 0, v[64:65]
	v_lshl_add_u64 v[64:65], v[70:71], 0, s[72:73]
	v_lshl_add_u64 v[70:71], v[70:71], 0, s[4:5]
	global_load_dwordx4 v[144:147], v[66:67], off
	global_load_dwordx4 v[148:151], v[68:69], off
	global_load_dwordx4 v[152:155], v[70:71], off
	global_load_dwordx4 v[156:159], v[64:65], off
	v_lshl_add_u64 v[64:65], s[12:13], 0, v[188:189]
	global_load_dwordx2 v[180:181], v[64:65], off
	v_lshl_add_u64 v[188:189], v[188:189], 0, 8
	v_lshl_add_u64 v[190:191], v[190:191], 0, s[72:73]
	v_add_u32_e32 v192, 64, v192
	v_add_u32_e32 v194, 64, v194
.Lad_1545:
	s_add_i32 s7, s6, 1
	s_cmp_lt_u32 s7, s22
	s_cselect_b64 s[0:1], -1, 0
	s_add_i32 s4, s6, 2
	s_cmp_ge_u32 s4, s22
	s_cbranch_scc1 .Lad_1551
	v_ashrrev_i32_e32 v195, 31, v194
	v_ashrrev_i32_e32 v193, 31, v192
	v_lshlrev_b64 v[64:65], 9, v[194:195]
	v_lshl_add_u64 v[66:67], v[182:183], 0, v[64:65]
	v_lshlrev_b64 v[64:65], 9, v[192:193]
	v_lshl_add_u64 v[70:71], s[12:13], 0, v[190:191]
	s_mov_b64 s[4:5], 0x8200
	v_lshl_add_u64 v[68:69], v[182:183], 0, v[64:65]
	v_lshl_add_u64 v[64:65], v[70:71], 0, s[72:73]
	v_lshl_add_u64 v[70:71], v[70:71], 0, s[4:5]
	s_bitcmp1_b32 s6, 0
	s_cbranch_scc1 .Lad_ldA
	global_load_dwordx4 v[128:131], v[66:67], off
	global_load_dwordx4 v[132:135], v[68:69], off
	global_load_dwordx4 v[136:139], v[70:71], off
	global_load_dwordx4 v[140:143], v[64:65], off
	v_lshl_add_u64 v[64:65], s[12:13], 0, v[188:189]
	global_load_dwordx2 v[184:185], v[64:65], off
	s_branch .Lad_1551

; __device__ __forceinline__ void attn_unit(const Frame& F, int l, int samp, int b, int c, int g) {
;     ...
;         if (t + 1 < ntiles) ATT_LOAD(t + 1);
;         ATT_COMPUTE(buf, mwc);
;         if (t + 1 < ntiles) ATT_WRITE(buf ^ 1, t + 1);
.Latt2_norescale:
	ds_read2_b64 v[68:71], v215 offset0:4 offset1:6
	ds_read2_b64 v[72:75], v214 offset0:36 offset1:38
	ds_read2_b64 v[76:79], v195 offset0:68 offset1:70
	ds_read2_b64 v[202:205], v193 offset0:100 offset1:102
	s_andn2_b64 vcc, exec, s[0:1]
	v_mfma_f32_32x32x16_bf16 v[48:63], v[172:175], v[64:67], v[48:63]
	v_mfma_f32_32x32x16_bf16 v[32:47], v[168:171], v[64:67], v[32:47]
	v_mfma_f32_32x32x16_bf16 v[16:31], v[164:167], v[64:67], v[16:31]
	v_mfma_f32_32x32x16_bf16 v[0:15], v[160:163], v[64:67], v[0:15]
	v_cvt_pk_bf16_f32 v64, v90, v91
	v_cvt_pk_bf16_f32 v65, v92, v93
	v_cvt_pk_bf16_f32 v66, v94, v95
	v_cvt_pk_bf16_f32 v67, v196, v197
	ds_read2_b64 v[160:163], v215 offset0:8 offset1:10
	ds_read2_b64 v[164:167], v214 offset0:40 offset1:42
	ds_read2_b64 v[168:171], v195 offset0:72 offset1:74
	ds_read2_b64 v[172:175], v193 offset0:104 offset1:106
	s_waitcnt lgkmcnt(4)
	s_nop 0
	v_mfma_f32_32x32x16_bf16 v[48:63], v[68:71], v[64:67], v[48:63]
	v_mfma_f32_32x32x16_bf16 v[32:47], v[72:75], v[64:67], v[32:47]
	v_mfma_f32_32x32x16_bf16 v[16:31], v[76:79], v[64:67], v[16:31]
	v_mfma_f32_32x32x16_bf16 v[0:15], v[202:205], v[64:67], v[0:15]
	v_cvt_pk_bf16_f32 v64, v216, v217
	v_cvt_pk_bf16_f32 v65, v218, v219
	v_cvt_pk_bf16_f32 v66, v220, v221
	v_cvt_pk_bf16_f32 v67, v242, v243
	ds_read2_b64 v[68:71], v215 offset0:12 offset1:14
	ds_read2_b64 v[72:75], v214 offset0:44 offset1:46
	ds_read2_b64 v[76:79], v195 offset0:76 offset1:78
	ds_read2_b64 v[202:205], v193 offset0:108 offset1:110
	s_waitcnt lgkmcnt(4)
	s_waitcnt lgkmcnt(0)
	v_mfma_f32_32x32x16_bf16 v[48:63], v[160:163], v[64:67], v[48:63]
	v_mfma_f32_32x32x16_bf16 v[32:47], v[164:167], v[64:67], v[32:47]
	v_mfma_f32_32x32x16_bf16 v[16:31], v[168:171], v[64:67], v[16:31]
	v_mfma_f32_32x32x16_bf16 v[0:15], v[172:175], v[64:67], v[0:15]
	v_cvt_pk_bf16_f32 v64, v244, v245
	v_cvt_pk_bf16_f32 v65, v246, v247
	v_cvt_pk_bf16_f32 v66, v248, v249
	v_cvt_pk_bf16_f32 v67, v250, v251
	s_nop 1
	v_mfma_f32_32x32x16_bf16 v[48:63], v[68:71], v[64:67], v[48:63]
	v_mfma_f32_32x32x16_bf16 v[32:47], v[72:75], v[64:67], v[32:47]
	v_mfma_f32_32x32x16_bf16 v[16:31], v[76:79], v[64:67], v[16:31]
	v_mfma_f32_32x32x16_bf16 v[0:15], v[202:205], v[64:67], v[0:15]
	s_cbranch_vccnz .Lad_1555
	s_add_i32 s0, s6, 2
	s_cmp_lt_u32 s0, s22
	s_cbranch_scc1 .Lad_w5
	s_waitcnt vmcnt(0)
	s_branch .Lad_w
.Lad_w5:
	s_waitcnt vmcnt(5)
.Lad_w:
	s_bitcmp1_b32 s6, 0
	s_cbranch_scc1 .Lad_wB
	v_mov_b64_e32 v[68:69], v[144:145]
	v_mov_b64_e32 v[70:71], v[146:147]
	v_mov_b64_e32 v[76:77], v[148:149]
	v_mov_b64_e32 v[78:79], v[150:151]
	v_mov_b64_e32 v[64:65], v[156:157]
	v_mov_b64_e32 v[66:67], v[158:159]
	v_mov_b64_e32 v[72:73], v[152:153]
	v_mov_b64_e32 v[74:75], v[154:155]
	s_branch .Lad_1554
.Lad_wB:
	v_mov_b64_e32 v[68:69], v[128:129]
	v_mov_b64_e32 v[70:71], v[130:131]
	v_mov_b64_e32 v[76:77], v[132:133]
	v_mov_b64_e32 v[78:79], v[134:135]
	v_mov_b64_e32 v[64:65], v[140:141]
	v_mov_b64_e32 v[66:67], v[142:143]
	v_mov_b64_e32 v[72:73], v[136:137]
	v_mov_b64_e32 v[74:75], v[138:139]

; __device__ __forceinline__ void attn_unit(const Frame& F, int l, int samp, int b, int c, int g) {
;     ...
;         if (t + 1 < ntiles) ATT_WRITE(buf ^ 1, t + 1);
;         mwc = mwn; asm volatile("" : "+v"(mwc));
;         __syncthreads();
;     }
.Lad_1555:
	v_add_f32_e32 v64, 0, v82
	v_add_f32_e32 v64, v83, v64
	v_add_f32_e32 v64, v84, v64
	v_add_f32_e32 v64, v85, v64
	v_add_f32_e32 v64, v86, v64
	v_add_f32_e32 v64, v87, v64
	v_add_f32_e32 v64, v88, v64
	v_add_f32_e32 v64, v89, v64
	v_add_f32_e32 v64, v90, v64
	v_add_f32_e32 v64, v91, v64
	v_add_f32_e32 v64, v92, v64
	v_add_f32_e32 v64, v93, v64
	v_add_f32_e32 v64, v94, v64
	v_add_f32_e32 v64, v95, v64
	v_add_f32_e32 v64, v196, v64
	v_add_f32_e32 v64, v197, v64
	v_add_f32_e32 v64, v216, v64
	v_add_f32_e32 v64, v217, v64
	v_add_f32_e32 v64, v218, v64
	v_add_f32_e32 v64, v219, v64
	v_add_f32_e32 v64, v220, v64
	v_add_f32_e32 v64, v221, v64
	v_add_f32_e32 v64, v242, v64
	v_add_f32_e32 v64, v243, v64
	v_add_f32_e32 v64, v244, v64
	v_add_f32_e32 v64, v245, v64
	v_add_f32_e32 v64, v246, v64
	v_add_f32_e32 v64, v247, v64
	v_add_f32_e32 v64, v248, v64
	v_add_f32_e32 v64, v249, v64
	v_add_f32_e32 v64, v250, v64
	v_add_f32_e32 v64, v251, v64
	v_fmac_f32_e32 v64, v213, v80
	s_bitcmp1_b32 s6, 0
	s_cbranch_scc1 .Lad_mB
	v_mov_b64_e32 v[196:197], v[180:181]
	s_branch .Lad_m
.Lad_mB:
	v_mov_b64_e32 v[196:197], v[184:185]
.Lad_m:
	v_lshl_add_u64 v[188:189], v[188:189], 0, 8
	v_lshl_add_u64 v[190:191], v[190:191], 0, s[72:73]
	v_add_u32_e32 v192, 64, v192
	v_add_u32_e32 v194, 64, v194
	s_cmp_lg_u32 s22, s7
	v_add_u32_e32 v200, 0x4000, v200
	s_waitcnt lgkmcnt(0)
	s_barrier
	s_cbranch_scc0 .LBB0_1557
	v_mov_b32_e32 v216, v81
	v_mov_b32_e32 v213, v64
	s_mov_b32 s6, s7
	s_branch .Lad_1545
